# v65 + retention: next step's V rows requested one segment earlier (start of the causal-mask stage instead of the inner-product stage)
# speedup vs baseline: 1.0066x; 1.0031x over previous
.Lret_d1_end:
	s_mov_b64 s[16:17], -1
	s_and_b64 vcc, exec, s[54:55]
	s_cbranch_vccz .LBB0_1003
	s_and_b64 vcc, exec, s[56:57]
	s_cbranch_vccz .Lre_nov
	s_add_i32 s82, s49, -1
	s_and_b64 s[96:97], s[44:45], exec
	s_cselect_b32 s82, s82, s33
	s_mov_b32 s32, 0xfffe0000
	s_cselect_b32 s32, 0x20000, s32
	s_lshl_b32 s82, s82, 19
	s_add_u32 s82, s42, s82
	s_addc_u32 s83, s43, 0
	v_sub_u32_e32 v8, 0x7f, v202
	v_lshlrev_b32_e32 v9, 1, v203
	v_cndmask_b32_e64 v8, v8, v202, s[44:45]
	v_lshl_or_b32 v8, v8, 12, v9
	v_add_u32_e32 v9, s32, v8
	v_add_u32_e32 v12, s32, v9
	v_add_u32_e32 v13, s32, v12
	global_load_dwordx4 v[160:163], v8, s[82:83]
	global_load_dwordx4 v[164:167], v9, s[82:83]
	global_load_dwordx4 v[168:171], v12, s[82:83]
	global_load_dwordx4 v[172:175], v13, s[82:83]
.Lre_nov:
	v_lshlrev_b32_e32 v4, 2, v233
	v_add_u32_e32 v2, v234, v205
	v_add_u32_e32 v5, v4, v209
	s_barrier
	v_add_u32_e32 v4, v4, v210
	v_sub_u32_e32 v7, v2, v5
	v_sub_u32_e32 v10, v2, v4
	v_mul_lo_u32 v3, v2, s68
	v_lshl_add_u32 v6, v5, 1, v3
	v_lshl_add_u32 v3, v4, 1, v3
	s_and_saveexec_b64 s[16:17], s[10:11]
	s_cbranch_execz .Lre_m1
	v_cmp_le_i32_e64 s[82:83], 0, v7
	v_cmp_le_i32_e64 s[96:97], 1, v7
	v_cmp_le_i32_e64 s[58:59], 2, v7
	v_cmp_le_i32_e32 vcc, 3, v7
	v_cndmask_b32_e64 v128, 0, v128, s[82:83]
	v_cndmask_b32_e64 v129, 0, v129, s[96:97]
	v_cndmask_b32_e64 v130, 0, v130, s[58:59]
	v_cndmask_b32_e32 v131, 0, v131, vcc
	v_cmp_le_i32_e64 s[82:83], 8, v7
	v_cmp_le_i32_e64 s[96:97], 9, v7
	v_cmp_le_i32_e64 s[58:59], 10, v7
	v_cmp_le_i32_e32 vcc, 11, v7
	v_cndmask_b32_e64 v132, 0, v132, s[82:83]
	v_cndmask_b32_e64 v133, 0, v133, s[96:97]
	v_cndmask_b32_e64 v134, 0, v134, s[58:59]
	v_cndmask_b32_e32 v135, 0, v135, vcc
	v_cmp_le_i32_e64 s[82:83], 16, v7
	v_cmp_le_i32_e64 s[96:97], 17, v7
	v_cmp_le_i32_e64 s[58:59], 18, v7
	v_cmp_le_i32_e32 vcc, 19, v7
	v_cndmask_b32_e64 v136, 0, v136, s[82:83]
	v_cndmask_b32_e64 v137, 0, v137, s[96:97]
	v_cndmask_b32_e64 v138, 0, v138, s[58:59]
	v_cndmask_b32_e32 v139, 0, v139, vcc
	v_cmp_le_i32_e64 s[82:83], 24, v7
	v_cmp_le_i32_e64 s[96:97], 25, v7
	v_cmp_le_i32_e64 s[58:59], 26, v7
	v_cmp_le_i32_e32 vcc, 27, v7
	v_cndmask_b32_e64 v140, 0, v140, s[82:83]
	v_cndmask_b32_e64 v141, 0, v141, s[96:97]
	v_cndmask_b32_e64 v142, 0, v142, s[58:59]
	v_cndmask_b32_e32 v143, 0, v143, vcc

.Lre_m2:
	s_or_b64 exec, exec, s[16:17]
	v_cvt_pk_bf16_f32 v8, v112, v113
	v_cvt_pk_bf16_f32 v9, v114, v115
	ds_write_b64 v3, v[8:9]
	v_cvt_pk_bf16_f32 v12, v116, v117
	v_cvt_pk_bf16_f32 v13, v118, v119
	ds_write_b64 v3, v[12:13] offset:16
	v_cvt_pk_bf16_f32 v8, v120, v121
	v_cvt_pk_bf16_f32 v9, v122, v123
	ds_write_b64 v3, v[8:9] offset:32
	v_cvt_pk_bf16_f32 v12, v124, v125
	v_cvt_pk_bf16_f32 v13, v126, v127
	ds_write_b64 v3, v[12:13] offset:48
	s_and_b64 vcc, exec, s[56:57]
	s_waitcnt lgkmcnt(0)
	s_barrier
.LBB0_974:
	s_and_b64 vcc, exec, s[46:47]
	s_cbranch_vccz .Lret_nopf
	s_add_u32 s16, s40, s28
	s_addc_u32 s17, s41, s34
	s_lshl_b64 s[16:17], s[16:17], 12
	s_or_b32 s16, s16, s80
	s_add_u32 s16, s26, s16
	s_addc_u32 s17, s27, s17
	v_sub_u32_e32 v2, 0x7f, v197
	v_lshlrev_b32_e32 v3, 1, v203
	v_lshl_or_b32 v2, v2, 12, v3
	global_load_dwordx4 v[124:127], v2, s[16:17]
	v_add_u32_e32 v3, 0xfffe0000, v2
	global_load_dwordx4 v[128:131], v3, s[16:17]
	v_add_u32_e32 v4, 0xfffe0000, v3
	global_load_dwordx4 v[132:135], v4, s[16:17]
	v_add_u32_e32 v5, 0xfffe0000, v4
	global_load_dwordx4 v[136:139], v5, s[16:17]
